# diff kt-loop unrolled by two (even/odd tile = LDS stage baked into ds_read immediates; 13 address VALU + even-tile control removed), on top of v51
# speedup vs baseline: 1.0145x; 1.0145x over previous
; DI void diff_item(const Params& P, char* lds, int layer, int pair, int qt, int& tab_head) {
;     ...
;     const unsigned lds0 = (unsigned)(uintptr_t)lds;
;     int goff[2];
; #pragma unroll
;     for (int i = 0; i < 2; ++i) goff[i] = (8 * w + 4 * i + (lane >> 4)) * PO + (((lane & 15) ^ (((lane >> 4) << 2) | ((2 * w + i) & 3))) * 8);
;     const u16* kg = base + head * 128 + OFF_CK;
;     const u16* vg = base + head * 128 + OFF_CV;
;     auto issue = [&](int kt, int buf) {
;         const size_t to = (size_t)(64 * kt) * PO;
; #pragma unroll
;         for (int i = 0; i < 2; ++i) {
;             glds16(kg + to + goff[i], (unsigned)__builtin_amdgcn_readfirstlane(lds0 + buf * 32768 + (2 * w + i) * 1024));
;             glds16(vg + to + goff[i], (unsigned)__builtin_amdgcn_readfirstlane(lds0 + buf * 32768 + 16384 + (2 * w + i) * 1024));
;         }
;     };
;     issue(0, 0);
;     bf16x8 qf[4];
; #pragma unroll
;     for (int s = 0; s < 4; ++s) qf[s] = *(const bf16x8*)(base + (size_t)qpos * PO + OFF_CQ + head * 128 + mp * 64 + 16 * s + 8 * hh);
;     float m = -1e30f, l = 0.f;
;     f32x16 O[4];
; #pragma unroll
;     for (int dt = 0; dt < 4; ++dt)
; #pragma unroll
;         for (int i = 0; i < 16; ++i) O[dt][i] = 0.f;
;     const int sig_r = ((r & 3) << 2) | ((r >> 2) & 3);
;     const int kx0 = (8 * mp + hh) ^ sig_r;
;     const int i16 = lane & 15, q = i16 >> 2, pp = i16 & 3, blk = (lane >> 4) & 1;
;     const int vl0 = (4 * hh + q) * 256 + (16 * ((q << 2) | (blk << 1) | ((pp >> 1) ^ hh)) + 8 * (pp & 1));
;     const int nkt = 2 * qt + 2;
.LBB0_250:
	s_or_b64 exec, exec, s[0:1]
	v_ashrrev_i32_e32 v169, 6, v168
	v_mov_b64_e32 v[2:3], s[20:21]
	s_waitcnt vmcnt(0)
	flat_load_dword v198, v[2:3]
	v_bfe_u32 v2, v168, 4, 2
	v_lshlrev_b32_e32 v7, 1, v169
	v_lshl_or_b32 v3, v169, 3, v2
	v_lshlrev_b32_e32 v2, 2, v2
	v_and_b32_e32 v7, 2, v7
	v_and_b32_e32 v6, 15, v168
	v_or_b32_e32 v9, v7, v2
	v_mul_lo_u32 v3, v3, s67
	v_bitop3_b32 v2, v7, v6, v2 bitop3:0x36
	v_bitop3_b32 v6, v9, v6, 1 bitop3:0x36
	v_lshl_or_b32 v2, v2, 3, v3
	v_lshlrev_b32_e32 v6, 3, v6
	s_sub_i32 s22, 63, s25
	v_add3_u32 v6, v3, v6, s43
	v_ashrrev_i32_e32 v3, 31, v2
	v_lshlrev_b64 v[170:171], 1, v[2:3]
	v_lshlrev_b32_e32 v9, 11, v169
	s_cmp_lg_u32 0, -1
	v_lshl_add_u64 v[2:3], s[96:97], 0, v[170:171]
	v_readfirstlane_b32 s0, v9
	s_cselect_b32 s23, 0, 0
	v_ashrrev_i32_e32 v7, 31, v6
	v_and_b32_e32 v194, 3, v169
	s_add_i32 s1, s0, s23
	s_mov_b32 s16, m0
	s_mov_b32 m0, s1
	s_nop 0
	global_load_lds_dwordx4 v[2:3], off
	s_mov_b32 m0, s16
	v_lshl_add_u64 v[2:3], s[14:15], 0, v[170:171]
	s_add_i32 s40, s23, 0x4000
	v_lshlrev_b64 v[172:173], 1, v[6:7]
	v_lshlrev_b32_e32 v5, 5, v194
	s_add_i32 s1, s0, s40
	s_mov_b32 s16, m0
	s_mov_b32 m0, s1
	s_nop 0
	global_load_lds_dwordx4 v[2:3], off
	s_mov_b32 m0, s16
	v_lshl_add_u64 v[2:3], s[96:97], 0, v[172:173]
	s_add_i32 s41, s23, 0x400
	v_and_b32_e32 v195, 31, v168
	v_lshl_or_b32 v8, s22, 7, v5
	s_add_i32 s1, s0, s41
	s_mov_b32 s16, m0
	s_mov_b32 m0, s1
	s_nop 0
	global_load_lds_dwordx4 v[2:3], off
	s_mov_b32 m0, s16
	v_lshl_add_u64 v[2:3], s[14:15], 0, v[172:173]
	s_add_i32 s51, s23, 0x4400
	v_or_b32_e32 v0, v8, v195
	s_add_i32 s0, s0, s51
	s_mov_b32 s1, m0
	s_mov_b32 m0, s0
	s_nop 0
	global_load_lds_dwordx4 v[2:3], off
	s_mov_b32 m0, s1
	v_mov_b64_e32 v[2:3], s[58:59]
	v_mad_u64_u32 v[166:167], s[0:1], v0, s52, v[2:3]
	s_lshl_b32 s16, s24, 1
	v_ashrrev_i32_e32 v197, 8, v168
	v_lshl_add_u64 v[2:3], v[166:167], 0, s[16:17]
	s_mov_b64 s[0:1], 0x1b00
	v_lshl_add_u64 v[164:165], v[2:3], 0, s[0:1]
	v_lshlrev_b32_e32 v2, 6, v197
	v_bfe_u32 v196, v168, 5, 1
	v_ashrrev_i32_e32 v3, 31, v2
	v_lshl_add_u64 v[2:3], v[2:3], 1, v[164:165]
	v_lshlrev_b32_e32 v0, 4, v196
	v_lshl_add_u64 v[2:3], v[2:3], 0, v[0:1]
	flat_load_dwordx4 v[144:147], v[2:3]
	flat_load_dwordx4 v[148:151], v[2:3] offset:32
	flat_load_dwordx4 v[152:155], v[2:3] offset:64
	flat_load_dwordx4 v[156:159], v[2:3] offset:96
	v_bfe_u32 v2, v168, 2, 2
	v_and_or_b32 v3, v4, 12, v2
	v_lshlrev_b32_e32 v4, 3, v197
	v_lshlrev_b32_e32 v193, 2, v196
	v_lshrrev_b32_e32 v6, 3, v168
	v_lshrrev_b32_e32 v7, 1, v168
	v_bitop3_b32 v3, v4, v3, v196 bitop3:0x36
	v_or_b32_e32 v4, v193, v2
	v_lshlrev_b32_e32 v2, 2, v2
	v_and_b32_e32 v6, 2, v6
	v_bitop3_b32 v7, v7, v196, 1 bitop3:0x6c
	v_or3_b32 v2, v2, v6, v7
	v_lshlrev_b32_e32 v6, 3, v168
	v_and_b32_e32 v6, 8, v6
	v_lshlrev_b32_e32 v4, 8, v4
	v_lshl_or_b32 v2, v2, 4, v6
	s_movk_i32 s0, 0x60
	v_bitop3_b32 v212, v2, s0, v4 bitop3:0x36
	s_movk_i32 s0, 0x80
	v_bitop3_b32 v213, v2, s0, v4 bitop3:0x36
	s_movk_i32 s0, 0xa0
	v_bitop3_b32 v214, v2, s0, v4 bitop3:0x36
	s_movk_i32 s0, 0xc0
	v_bitop3_b32 v215, v2, s0, v4 bitop3:0x36
	s_movk_i32 s0, 0xe0
	v_bitop3_b32 v216, v2, s0, v4 bitop3:0x36
	s_lshl_b32 s0, s25, 7
	v_or_b32_e32 v199, v2, v4
	v_bitop3_b32 v210, v2, 32, v4 bitop3:0x36
	v_bitop3_b32 v211, v2, 64, v4 bitop3:0x36
	v_subrev_u32_e32 v2, s0, v5
	v_add_u32_e32 v217, 0x1f41, v2
	v_lshlrev_b32_e32 v2, 2, v195
	v_lshl_or_b32 v2, v194, 7, v2
	v_sub_u32_e32 v0, v2, v0
	s_lshl_b32 s0, s25, 9
	s_lshl_b32 s49, s22, 1
	v_lshlrev_b32_e32 v6, 8, v168
	v_subrev_u32_e32 v0, s0, v0
	s_add_i32 s0, 0, 0x27e14
	v_mov_b32_e32 v14, v1
	v_mov_b32_e32 v15, v1
	s_add_i32 s49, s49, 2
	v_or_b32_e32 v200, 31, v8
	v_and_b32_e32 v201, 0x1f00, v6
	v_lshlrev_b32_e32 v202, 4, v3
	v_add_u32_e32 v206, s23, v9
	v_add_u32_e32 v207, s40, v9
	v_add_u32_e32 v208, s41, v9
	v_add_u32_e32 v209, s51, v9
	v_add_u32_e32 v218, s0, v0
	v_mov_b32_e32 v0, v1
	v_mov_b32_e32 v2, v1
	v_mov_b32_e32 v3, v1
	v_mov_b32_e32 v4, v1
	v_mov_b32_e32 v5, v1
	v_mov_b32_e32 v6, v1
	v_mov_b32_e32 v7, v1
	v_mov_b32_e32 v8, v1
	v_mov_b32_e32 v9, v1
	v_mov_b32_e32 v10, v1
	v_mov_b32_e32 v11, v1
	v_mov_b32_e32 v12, v1
	v_mov_b32_e32 v13, v1
	v_mov_b64_e32 v[30:31], v[14:15]
	v_mov_b64_e32 v[46:47], v[14:15]
	v_mov_b64_e32 v[62:63], v[14:15]
	v_mov_b64_e32 v[78:79], v[14:15]
	v_xor_b32_e32 v203, 32, v202
	s_mov_b32 s50, 64
	v_xor_b32_e32 v204, 64, v202
	v_xor_b32_e32 v205, 0x60, v202
	s_max_u32 s51, s49, 1
	v_mov_b32_e32 v219, 0
	v_mov_b32_e32 v226, 0xf149f2ca
	s_mov_b32 s25, 0x8000
	v_mov_b32_e32 v220, 0
	s_mov_b64 s[0:1], 0
	v_mov_b64_e32 v[28:29], v[12:13]
	v_mov_b64_e32 v[26:27], v[10:11]
	v_mov_b64_e32 v[24:25], v[8:9]
	v_mov_b64_e32 v[22:23], v[6:7]
	v_mov_b64_e32 v[20:21], v[4:5]
	v_mov_b64_e32 v[18:19], v[2:3]
	v_mov_b64_e32 v[16:17], v[0:1]
	v_mov_b64_e32 v[44:45], v[12:13]
	v_mov_b64_e32 v[42:43], v[10:11]
	v_mov_b64_e32 v[40:41], v[8:9]
	v_mov_b64_e32 v[38:39], v[6:7]
	v_mov_b64_e32 v[36:37], v[4:5]
	v_mov_b64_e32 v[34:35], v[2:3]
	v_mov_b64_e32 v[32:33], v[0:1]
	v_mov_b64_e32 v[60:61], v[12:13]
	v_mov_b64_e32 v[58:59], v[10:11]
	v_mov_b64_e32 v[56:57], v[8:9]
	v_mov_b64_e32 v[54:55], v[6:7]
	v_mov_b64_e32 v[52:53], v[4:5]
	v_mov_b64_e32 v[50:51], v[2:3]
	v_mov_b64_e32 v[48:49], v[0:1]
	v_mov_b64_e32 v[76:77], v[12:13]
	v_mov_b64_e32 v[74:75], v[10:11]
	v_mov_b64_e32 v[72:73], v[8:9]
	v_mov_b64_e32 v[70:71], v[6:7]
	v_mov_b64_e32 v[68:69], v[4:5]
	v_mov_b64_e32 v[66:67], v[2:3]
	v_mov_b64_e32 v[64:65], v[0:1]
	v_readfirstlane_b32 s63, v206
	s_add_u32 s64, s96, 0xe0000
	s_addc_u32 s65, s97, 0
	s_add_u32 s70, s14, 0xe0000
	s_addc_u32 s71, s15, 0
	s_mov_b32 s73, m0
	v_add_u32_e32 v14, v201, v202
	v_add_u32_e32 v15, v201, v203
	v_add_u32_e32 v221, v201, v204
	v_add_u32_e32 v222, v201, v205
	s_branch .Ldu_A
; #define LAS __attribute__((address_space(3)))
; #define MFMA(a, b, c) __builtin_amdgcn_mfma_f32_32x32x16_bf16((a), (b), (c), 0, 0, 0)
; template <typename F>
; DI void diff_step(lptr sK, lptr sV, int kx0, int vl0, const bf16x8 (&qf)[4], float& m, float& l, f32x16 (&O)[4],
;                   const LAS float* tb, bool far, float cfar, int lane, F&& mid) {
;     ...
;     lptr kr = sK + r * 256;
;     bf16x8 kf[8];
; #pragma unroll
;     for (int s = 0; s < 4; ++s) {
;         const int co = (kx0 ^ (2 * s)) * 16;
;         kf[2 * s] = *(const LAS bf16x8*)(kr + co);
;         kf[2 * s + 1] = *(const LAS bf16x8*)(kr + 8192 + co);
;     }
;     __builtin_amdgcn_sched_barrier(0);
;     mid();
;     __builtin_amdgcn_sched_barrier(0);
; #pragma unroll
;     for (int s = 0; s < 4; ++s) { p0 = MFMA(kf[2 * s], qf[s], p0); p1 = MFMA(kf[2 * s + 1], qf[s], p1); }
.Ldu_A:
	s_waitcnt vmcnt(0)
	s_waitcnt lgkmcnt(0)
	s_barrier
	ds_read_b128 v[80:83], v14
	ds_read_b128 v[84:87], v14 offset:8192
	ds_read_b128 v[120:123], v15
	ds_read_b128 v[6:9], v15 offset:8192
	ds_read_b128 v[116:119], v221
	ds_read_b128 v[2:5], v221 offset:8192
	ds_read_b128 v[10:13], v222
	ds_read_b128 v[112:115], v222 offset:8192
	v_add_u32_e32 v220, 1, v220
	s_add_u32 s72, s63, 0x8000
	s_mov_b32 m0, s72
	s_nop 0
	global_load_lds_dwordx4 v170, s[64:65]
	s_add_u32 s72, s63, 0xc000
	s_mov_b32 m0, s72
	s_nop 0
	global_load_lds_dwordx4 v170, s[70:71]
	s_add_u32 s72, s63, 0x8400
	s_mov_b32 m0, s72
	s_nop 0
	global_load_lds_dwordx4 v172, s[64:65]
	s_add_u32 s72, s63, 0xc400
	s_mov_b32 m0, s72
	s_nop 0
	global_load_lds_dwordx4 v172, s[70:71]
	s_add_u32 s64, s64, 0xe0000
	s_addc_u32 s65, s65, 0
	s_add_u32 s70, s70, 0xe0000
	s_addc_u32 s71, s71, 0
	v_cmp_gt_i32_e32 vcc, s42, v217
	s_waitcnt lgkmcnt(7)
	v_mfma_f32_32x32x16_bf16 v[96:111], v[80:83], v[144:147], 0
	s_waitcnt lgkmcnt(6)
	v_mfma_f32_32x32x16_bf16 v[80:95], v[84:87], v[144:147], 0
	s_waitcnt lgkmcnt(5)
	v_mfma_f32_32x32x16_bf16 v[96:111], v[120:123], v[148:151], v[96:111]
	s_waitcnt lgkmcnt(4)
	v_mfma_f32_32x32x16_bf16 v[80:95], v[6:9], v[148:151], v[80:95]
	s_waitcnt lgkmcnt(3)
	v_mfma_f32_32x32x16_bf16 v[96:111], v[116:119], v[152:155], v[96:111]
	s_waitcnt lgkmcnt(2)
	v_mfma_f32_32x32x16_bf16 v[80:95], v[2:5], v[152:155], v[80:95]
	ds_read_b64_tr_b16 v[2:3], v199 offset:16384
	ds_read_b64_tr_b16 v[4:5], v210 offset:18432
	ds_read_b64_tr_b16 v[6:7], v211 offset:16384
	ds_read_b64_tr_b16 v[8:9], v212 offset:18432
	s_waitcnt lgkmcnt(5)
	v_mfma_f32_32x32x16_bf16 v[96:111], v[10:13], v[156:159], v[96:111]
	ds_read_b64_tr_b16 v[10:11], v213 offset:16384
	ds_read_b64_tr_b16 v[12:13], v214 offset:18432
	ds_read_b64_tr_b16 v[160:161], v215 offset:16384
	ds_read_b64_tr_b16 v[162:163], v216 offset:18432
	s_waitcnt lgkmcnt(8)
	v_mfma_f32_32x32x16_bf16 v[80:95], v[112:115], v[156:159], v[80:95]
	v_max_f32_e32 v228, v226, v226
	s_and_saveexec_b64 s[22:23], vcc
	s_xor_b64 s[22:23], exec, s[22:23]
	s_cbranch_execz .LBB0_258_a
	ds_read2_b32 v[112:113], v218 offset0:58 offset1:59
	ds_read2_b32 v[114:115], v218 offset0:56 offset1:57
	ds_read2_b32 v[116:117], v218 offset0:50 offset1:51
	ds_read2_b32 v[118:119], v218 offset0:48 offset1:49
	ds_read2_b32 v[120:121], v218 offset0:26 offset1:27
	ds_read2_b32 v[122:123], v218 offset0:24 offset1:25
	ds_read2_b32 v[124:125], v218 offset0:18 offset1:19
	ds_read2_b32 v[126:127], v218 offset0:16 offset1:17
	ds_read2_b32 v[128:129], v218 offset0:42 offset1:43
	ds_read2_b32 v[130:131], v218 offset0:40 offset1:41
	ds_read2_b32 v[132:133], v218 offset0:34 offset1:35
	ds_read2_b32 v[134:135], v218 offset0:32 offset1:33
	ds_read2_b32 v[136:137], v218 offset0:10 offset1:11
	ds_read2_b32 v[138:139], v218 offset0:8 offset1:9
	ds_read2_b32 v[140:141], v218 offset0:2 offset1:3
	ds_read2_b32 v[142:143], v218 offset1:1
	s_nop 7
	s_nop 7
	s_nop 3
	s_waitcnt lgkmcnt(14)
	v_fma_f32 v96, v96, v178, v113
	s_waitcnt lgkmcnt(11)
	v_fma_f32 v80, v80, v178, v121
	v_fma_f32 v97, v97, v178, v112
	v_fma_f32 v81, v81, v178, v120
	v_fma_f32 v98, v98, v178, v115
	s_waitcnt lgkmcnt(10)
	v_fma_f32 v82, v82, v178, v123
	v_fma_f32 v99, v99, v178, v114
	v_fma_f32 v83, v83, v178, v122
	v_max3_f32 v112, v96, v97, v80
	v_fma_f32 v100, v100, v178, v117
	v_fma_f32 v101, v101, v178, v116
	v_fma_f32 v102, v102, v178, v119
	s_nop 0
	v_max3_f32 v113, v98, v99, v81
	v_fma_f32 v103, v103, v178, v118
	v_max3_f32 v112, v112, v82, v83
	s_waitcnt lgkmcnt(9)
	v_fma_f32 v84, v84, v178, v125
	v_fma_f32 v85, v85, v178, v124
	s_waitcnt lgkmcnt(8)
	v_fma_f32 v86, v86, v178, v127
	v_fma_f32 v87, v87, v178, v126
	v_max3_f32 v113, v113, v102, v103
	v_max3_f32 v112, v112, v100, v101
	s_waitcnt lgkmcnt(7)
	v_fma_f32 v104, v104, v178, v129
	v_fma_f32 v105, v105, v178, v128
	s_waitcnt lgkmcnt(6)
	v_fma_f32 v106, v106, v178, v131
	v_fma_f32 v107, v107, v178, v130
	v_max3_f32 v113, v113, v86, v87
	v_max3_f32 v112, v112, v84, v85
	s_waitcnt lgkmcnt(3)
	v_fma_f32 v88, v88, v178, v137
	v_fma_f32 v89, v89, v178, v136
	s_waitcnt lgkmcnt(2)
	v_fma_f32 v90, v90, v178, v139
	v_fma_f32 v91, v91, v178, v138
	v_max3_f32 v113, v113, v106, v107
	v_max3_f32 v112, v112, v104, v105
	v_fma_f32 v108, v108, v178, v133
	v_fma_f32 v109, v109, v178, v132
	v_fma_f32 v110, v110, v178, v135
	v_fma_f32 v111, v111, v178, v134
	s_nop 0
	v_max3_f32 v113, v113, v90, v91
	v_max3_f32 v112, v112, v88, v89
	s_waitcnt lgkmcnt(1)
	v_fma_f32 v92, v92, v178, v141
	v_fma_f32 v93, v93, v178, v140
	s_waitcnt lgkmcnt(0)
	v_fma_f32 v94, v94, v178, v143
	v_fma_f32 v95, v95, v178, v142
	v_max3_f32 v113, v113, v110, v111
	v_max3_f32 v112, v112, v108, v109
	s_nop 0
	v_max3_f32 v112, v112, v92, v93
	v_max3_f32 v113, v113, v94, v95
	s_nop 0
	v_max_f32_e32 v113, v113, v113
	v_max_f32_e32 v112, v112, v112
	v_max_f32_e32 v112, v112, v113
	v_mov_b32_e32 v113, v112
	s_nop 1
	v_permlane32_swap_b32_e32 v112, v113
	v_max_f32_e32 v113, v113, v113
	v_max_f32_e32 v112, v112, v112
	v_max_f32_e32 v112, v112, v113
	v_sub_f32_e32 v113, v112, v226
	v_cmp_lt_f32_e32 vcc, s45, v113
	s_cmp_eq_u64 vcc, 0
	v_max_f32_e32 v112, v228, v112
	s_cselect_b64 vcc, -1, 0
	v_cndmask_b32_e32 v227, v112, v226, vcc
	v_sub_f32 v112, v96, v227
	v_sub_f32 v128, v80, v227
	v_sub_f32 v113, v97, v227
	v_sub_f32 v129, v81, v227
	v_sub_f32 v114, v98, v227
	v_sub_f32 v130, v82, v227
	v_sub_f32 v115, v99, v227
	v_sub_f32 v131, v83, v227
	v_sub_f32 v116, v100, v227
	v_sub_f32 v132, v84, v227
	v_sub_f32 v117, v101, v227
	v_sub_f32 v133, v85, v227
	v_sub_f32 v118, v102, v227
	v_sub_f32 v134, v86, v227
	v_sub_f32 v119, v103, v227
	v_sub_f32 v135, v87, v227
	v_sub_f32 v120, v104, v227
	v_sub_f32 v136, v88, v227
	v_sub_f32 v121, v105, v227
	v_sub_f32 v137, v89, v227
	v_sub_f32 v122, v106, v227
	v_sub_f32 v138, v90, v227
	v_sub_f32 v123, v107, v227
	v_sub_f32 v139, v91, v227
	v_sub_f32 v124, v108, v227
	v_sub_f32 v140, v92, v227
	v_sub_f32 v125, v109, v227
	v_sub_f32 v141, v93, v227
	v_sub_f32 v126, v110, v227
	v_sub_f32 v142, v94, v227
	v_sub_f32 v127, v111, v227
	v_sub_f32 v143, v95, v227

.Ldf_far_nofix_a:
.LBB0_260_a:
	s_or_b64 exec, exec, s[22:23]
	v_cmp_neq_f32_e32 vcc, v227, v226
	ds_read_b64_tr_b16 v[80:81], v199 offset:20480
	ds_read_b64_tr_b16 v[82:83], v210 offset:22528
	ds_read_b64_tr_b16 v[84:85], v211 offset:20480
	ds_read_b64_tr_b16 v[86:87], v212 offset:22528
	ds_read_b64_tr_b16 v[88:89], v213 offset:20480
	ds_read_b64_tr_b16 v[90:91], v214 offset:22528
	ds_read_b64_tr_b16 v[92:93], v215 offset:20480
	ds_read_b64_tr_b16 v[94:95], v216 offset:22528
	v_exp_f32_e32 v104, v112
	v_exp_f32_e32 v105, v113
	v_exp_f32_e32 v106, v114
	v_exp_f32_e32 v107, v115
	v_exp_f32_e32 v108, v116
	v_exp_f32_e32 v109, v117
	v_exp_f32_e32 v110, v118
	v_exp_f32_e32 v111, v119
	s_cbranch_vccz .Ldf_norescale_a
	v_sub_f32_e32 v246, v226, v227
	v_exp_f32_e32 v246, v246
	s_nop 0
	v_mul_f32_e32 v219, v219, v246
	v_pk_mul_f32 v[78:79], v[78:79], v[246:247] op_sel_hi:[1,0]
	v_pk_mul_f32 v[76:77], v[76:77], v[246:247] op_sel_hi:[1,0]
	v_pk_mul_f32 v[74:75], v[74:75], v[246:247] op_sel_hi:[1,0]
	v_pk_mul_f32 v[72:73], v[72:73], v[246:247] op_sel_hi:[1,0]
	v_pk_mul_f32 v[70:71], v[70:71], v[246:247] op_sel_hi:[1,0]
	v_pk_mul_f32 v[68:69], v[68:69], v[246:247] op_sel_hi:[1,0]
	v_pk_mul_f32 v[66:67], v[66:67], v[246:247] op_sel_hi:[1,0]
	v_pk_mul_f32 v[64:65], v[64:65], v[246:247] op_sel_hi:[1,0]
	v_pk_mul_f32 v[62:63], v[62:63], v[246:247] op_sel_hi:[1,0]
	v_pk_mul_f32 v[60:61], v[60:61], v[246:247] op_sel_hi:[1,0]
	v_pk_mul_f32 v[58:59], v[58:59], v[246:247] op_sel_hi:[1,0]
	v_pk_mul_f32 v[56:57], v[56:57], v[246:247] op_sel_hi:[1,0]
	v_pk_mul_f32 v[54:55], v[54:55], v[246:247] op_sel_hi:[1,0]
	v_pk_mul_f32 v[52:53], v[52:53], v[246:247] op_sel_hi:[1,0]
	v_pk_mul_f32 v[50:51], v[50:51], v[246:247] op_sel_hi:[1,0]
	v_pk_mul_f32 v[48:49], v[48:49], v[246:247] op_sel_hi:[1,0]
	v_pk_mul_f32 v[46:47], v[46:47], v[246:247] op_sel_hi:[1,0]
	v_pk_mul_f32 v[44:45], v[44:45], v[246:247] op_sel_hi:[1,0]
	v_pk_mul_f32 v[42:43], v[42:43], v[246:247] op_sel_hi:[1,0]
	v_pk_mul_f32 v[40:41], v[40:41], v[246:247] op_sel_hi:[1,0]
	v_pk_mul_f32 v[38:39], v[38:39], v[246:247] op_sel_hi:[1,0]
	v_pk_mul_f32 v[36:37], v[36:37], v[246:247] op_sel_hi:[1,0]
	v_pk_mul_f32 v[34:35], v[34:35], v[246:247] op_sel_hi:[1,0]
	v_pk_mul_f32 v[32:33], v[32:33], v[246:247] op_sel_hi:[1,0]
	v_pk_mul_f32 v[30:31], v[30:31], v[246:247] op_sel_hi:[1,0]
	v_pk_mul_f32 v[28:29], v[28:29], v[246:247] op_sel_hi:[1,0]
	v_pk_mul_f32 v[26:27], v[26:27], v[246:247] op_sel_hi:[1,0]
	v_pk_mul_f32 v[24:25], v[24:25], v[246:247] op_sel_hi:[1,0]
	v_pk_mul_f32 v[22:23], v[22:23], v[246:247] op_sel_hi:[1,0]
	v_pk_mul_f32 v[20:21], v[20:21], v[246:247] op_sel_hi:[1,0]
	v_pk_mul_f32 v[18:19], v[18:19], v[246:247] op_sel_hi:[1,0]
	v_pk_mul_f32 v[16:17], v[16:17], v[246:247] op_sel_hi:[1,0]
.Ldf_norescale_a:
	v_add_f32_e32 v238, v104, v105
	v_add_f32_e32 v239, v106, v107
	v_add_f32_e32 v240, v108, v109
	v_add_f32_e32 v241, v110, v111
	v_add_f32_e32 v238, v238, v239
	v_add_f32_e32 v240, v240, v241
	v_cvt_pk_bf16_f32 v104, v104, v105
	v_cvt_pk_bf16_f32 v105, v106, v107
	v_cvt_pk_bf16_f32 v106, v108, v109
	v_cvt_pk_bf16_f32 v107, v110, v111
	v_add_f32_e32 v238, v238, v240
	v_add_f32_e32 v219, v219, v238
	s_waitcnt lgkmcnt(8)
	v_mfma_f32_32x32x16_bf16 v[64:79], v[2:5], v[104:107], v[64:79]
	v_exp_f32_e32 v96, v120
	v_exp_f32_e32 v97, v121
	v_exp_f32_e32 v98, v122
	v_exp_f32_e32 v99, v123
	v_mfma_f32_32x32x16_bf16 v[48:63], v[6:9], v[104:107], v[48:63]
	v_exp_f32_e32 v100, v124
	v_exp_f32_e32 v101, v125
	v_exp_f32_e32 v102, v126
	v_exp_f32_e32 v103, v127
	v_mfma_f32_32x32x16_bf16 v[32:47], v[10:13], v[104:107], v[32:47]
	v_add_f32_e32 v238, v96, v97
	v_add_f32_e32 v239, v98, v99
	v_add_f32_e32 v240, v100, v101
	v_add_f32_e32 v241, v102, v103
	v_add_f32_e32 v238, v238, v239
	v_add_f32_e32 v240, v240, v241
	v_mfma_f32_32x32x16_bf16 v[16:31], v[160:163], v[104:107], v[16:31]
	ds_read_b64_tr_b16 v[2:3], v199 offset:24576
	ds_read_b64_tr_b16 v[4:5], v210 offset:26624
	ds_read_b64_tr_b16 v[6:7], v211 offset:24576
	ds_read_b64_tr_b16 v[8:9], v212 offset:26624
	ds_read_b64_tr_b16 v[10:11], v213 offset:24576
	ds_read_b64_tr_b16 v[12:13], v214 offset:26624
	ds_read_b64_tr_b16 v[160:161], v215 offset:24576
	ds_read_b64_tr_b16 v[162:163], v216 offset:26624
	v_cvt_pk_bf16_f32 v96, v96, v97
	v_cvt_pk_bf16_f32 v97, v98, v99
	v_cvt_pk_bf16_f32 v98, v100, v101
	v_cvt_pk_bf16_f32 v99, v102, v103
	v_add_f32_e32 v238, v238, v240
	v_add_f32_e32 v219, v219, v238
	s_waitcnt lgkmcnt(8)
	v_mfma_f32_32x32x16_bf16 v[64:79], v[80:83], v[96:99], v[64:79]
	v_exp_f32_e32 v112, v128
	v_exp_f32_e32 v113, v129
	v_exp_f32_e32 v114, v130
	v_exp_f32_e32 v115, v131
	v_mfma_f32_32x32x16_bf16 v[48:63], v[84:87], v[96:99], v[48:63]
	v_exp_f32_e32 v116, v132
	v_exp_f32_e32 v117, v133
	v_exp_f32_e32 v118, v134
	v_exp_f32_e32 v119, v135
	v_mfma_f32_32x32x16_bf16 v[32:47], v[88:91], v[96:99], v[32:47]
	v_add_f32_e32 v238, v112, v113
	v_add_f32_e32 v239, v114, v115
	v_add_f32_e32 v240, v116, v117
	v_add_f32_e32 v241, v118, v119
	v_add_f32_e32 v238, v238, v239
	v_add_f32_e32 v240, v240, v241
	v_mfma_f32_32x32x16_bf16 v[16:31], v[92:95], v[96:99], v[16:31]
	ds_read_b64_tr_b16 v[80:81], v199 offset:28672
	ds_read_b64_tr_b16 v[82:83], v210 offset:30720
	ds_read_b64_tr_b16 v[84:85], v211 offset:28672
	ds_read_b64_tr_b16 v[86:87], v212 offset:30720
	ds_read_b64_tr_b16 v[88:89], v213 offset:28672
	ds_read_b64_tr_b16 v[90:91], v214 offset:30720
	ds_read_b64_tr_b16 v[92:93], v215 offset:28672
	ds_read_b64_tr_b16 v[94:95], v216 offset:30720
	v_cvt_pk_bf16_f32 v112, v112, v113
	v_cvt_pk_bf16_f32 v113, v114, v115
	v_cvt_pk_bf16_f32 v114, v116, v117
	v_cvt_pk_bf16_f32 v115, v118, v119
	v_add_f32_e32 v238, v238, v240
	v_add_f32_e32 v219, v219, v238
	s_waitcnt lgkmcnt(8)
; #define LAS __attribute__((address_space(3)))
; DI void diff_item(const Params& P, char* lds, int layer, int pair, int qt, int& tab_head) {
;     ...
;     auto issue = [&](int kt, int buf) {
;         const size_t to = (size_t)(64 * kt) * PO;
; #pragma unroll
;         for (int i = 0; i < 2; ++i) {
;             glds16(kg + to + goff[i], (unsigned)__builtin_amdgcn_readfirstlane(lds0 + buf * 32768 + (2 * w + i) * 1024));
;             glds16(vg + to + goff[i], (unsigned)__builtin_amdgcn_readfirstlane(lds0 + buf * 32768 + 16384 + (2 * w + i) * 1024));
;         }
;     };
;     ...
;     for (int kt = 0; kt < nkt; ++kt) {
;         asm volatile("s_waitcnt vmcnt(0)" ::: "memory");
;         __syncthreads();
;         auto mid = [&]() { if (kt + 1 < nkt) issue(kt + 1, (kt + 1) & 1); };
;         if (64 * kt <= q0 + 32 * qs + 31) {
;             const bool far = (q0 + 32 * qs) - (64 * kt + 63) >= 1536;
;             const LAS float* tb = (const LAS float*)ctab + (qpos - 64 * kt - 4 * hh + 64 - 63);
;             lptr bufp = (lptr)lds + (kt & 1) * 32768;
;             diff_step(bufp, bufp + 16384, kx0, vl0, qf, m, l, O, tb, far, cfar, lane, mid);
	v_mfma_f32_32x32x16_bf16 v[64:79], v[2:5], v[112:115], v[64:79]
	v_exp_f32_e32 v120, v136
	v_exp_f32_e32 v121, v137
	v_exp_f32_e32 v122, v138
	v_exp_f32_e32 v123, v139
	v_mfma_f32_32x32x16_bf16 v[48:63], v[6:9], v[112:115], v[48:63]
	v_exp_f32_e32 v124, v140
	v_exp_f32_e32 v125, v141
	v_exp_f32_e32 v126, v142
	v_exp_f32_e32 v127, v143
	v_mfma_f32_32x32x16_bf16 v[32:47], v[10:13], v[112:115], v[32:47]
	v_add_f32_e32 v238, v120, v121
	v_add_f32_e32 v239, v122, v123
	v_add_f32_e32 v240, v124, v125
	v_add_f32_e32 v241, v126, v127
	v_add_f32_e32 v238, v238, v239
	v_add_f32_e32 v240, v240, v241
	v_mfma_f32_32x32x16_bf16 v[16:31], v[160:163], v[112:115], v[16:31]
	v_cvt_pk_bf16_f32 v120, v120, v121
	v_cvt_pk_bf16_f32 v121, v122, v123
	v_cvt_pk_bf16_f32 v122, v124, v125
	v_cvt_pk_bf16_f32 v123, v126, v127
	v_add_f32_e32 v238, v238, v240
	v_add_f32_e32 v219, v219, v238
	s_waitcnt lgkmcnt(6)
	v_mfma_f32_32x32x16_bf16 v[64:79], v[80:83], v[120:123], v[64:79]
	s_waitcnt lgkmcnt(4)
	v_mfma_f32_32x32x16_bf16 v[48:63], v[84:87], v[120:123], v[48:63]
	s_waitcnt lgkmcnt(2)
	v_mfma_f32_32x32x16_bf16 v[32:47], v[88:91], v[120:123], v[32:47]
	s_waitcnt lgkmcnt(0)
	v_mfma_f32_32x32x16_bf16 v[16:31], v[92:95], v[120:123], v[16:31]
	s_add_i32 s50, s50, 64
	v_subrev_u32_e32 v217, 64, v217
	v_add_u32_e32 v218, 0xffffff00, v218
	v_mov_b32_e32 v226, v227
.Ldu_B:
	s_waitcnt vmcnt(0)
	s_sub_i32 s22, s50, 64
	v_cmp_le_u32_e32 vcc, s22, v200
	v_add_u32_e32 v0, 1, v220
	s_waitcnt lgkmcnt(0)
	s_barrier
	s_and_saveexec_b64 s[22:23], vcc
	s_xor_b64 s[40:41], exec, s[22:23]
	s_cbranch_execz .LBB0_263_b
	ds_read_b128 v[80:83], v14 offset:32768
	ds_read_b128 v[84:87], v14 offset:40960
	ds_read_b128 v[120:123], v15 offset:32768
	ds_read_b128 v[6:9], v15 offset:40960
	ds_read_b128 v[116:119], v221 offset:32768
	ds_read_b128 v[2:5], v221 offset:40960
	ds_read_b128 v[10:13], v222 offset:32768
	ds_read_b128 v[112:115], v222 offset:40960
	v_add_u32_e32 v220, 1, v220
	v_cmp_gt_u32_e32 vcc, s49, v220
	s_and_saveexec_b64 s[22:23], vcc
	s_cbranch_execz .LBB0_256_b
	s_mov_b32 s72, s63
	s_mov_b32 m0, s72
	s_nop 0
	global_load_lds_dwordx4 v170, s[64:65]
	s_add_u32 s72, s63, 0x4000
	s_mov_b32 m0, s72
	s_nop 0
	global_load_lds_dwordx4 v170, s[70:71]
	s_add_u32 s72, s63, 0x400
	s_mov_b32 m0, s72
	s_nop 0
	global_load_lds_dwordx4 v172, s[64:65]
	s_add_u32 s72, s63, 0x4400
	s_mov_b32 m0, s72
	s_nop 0
	global_load_lds_dwordx4 v172, s[70:71]
	s_add_u32 s64, s64, 0xe0000
	s_addc_u32 s65, s65, 0
	s_add_u32 s70, s70, 0xe0000
	s_addc_u32 s71, s71, 0
; #define LAS __attribute__((address_space(3)))
; #define MFMA(a, b, c) __builtin_amdgcn_mfma_f32_32x32x16_bf16((a), (b), (c), 0, 0, 0)
; template <typename F>
; DI void diff_step(lptr sK, lptr sV, int kx0, int vl0, const bf16x8 (&qf)[4], float& m, float& l, f32x16 (&O)[4],
;                   const LAS float* tb, bool far, float cfar, int lane, F&& mid) {
;     ...
;     lptr kr = sK + r * 256;
;     bf16x8 kf[8];
; #pragma unroll
;     for (int s = 0; s < 4; ++s) {
;         const int co = (kx0 ^ (2 * s)) * 16;
;         kf[2 * s] = *(const LAS bf16x8*)(kr + co);
;         kf[2 * s + 1] = *(const LAS bf16x8*)(kr + 8192 + co);
;     }
;     __builtin_amdgcn_sched_barrier(0);
;     mid();
;     __builtin_amdgcn_sched_barrier(0);
; #pragma unroll
;     for (int s = 0; s < 4; ++s) { p0 = MFMA(kf[2 * s], qf[s], p0); p1 = MFMA(kf[2 * s + 1], qf[s], p1); }
.LBB0_256_b:
	s_or_b64 exec, exec, s[22:23]
	v_cmp_gt_i32_e32 vcc, s42, v217
	s_waitcnt lgkmcnt(7)
	v_mfma_f32_32x32x16_bf16 v[96:111], v[80:83], v[144:147], 0
	s_waitcnt lgkmcnt(6)
	v_mfma_f32_32x32x16_bf16 v[80:95], v[84:87], v[144:147], 0
	s_waitcnt lgkmcnt(5)
	v_mfma_f32_32x32x16_bf16 v[96:111], v[120:123], v[148:151], v[96:111]
	s_waitcnt lgkmcnt(4)
	v_mfma_f32_32x32x16_bf16 v[80:95], v[6:9], v[148:151], v[80:95]
	s_waitcnt lgkmcnt(3)
	v_mfma_f32_32x32x16_bf16 v[96:111], v[116:119], v[152:155], v[96:111]
	s_waitcnt lgkmcnt(2)
	v_mfma_f32_32x32x16_bf16 v[80:95], v[2:5], v[152:155], v[80:95]
	ds_read_b64_tr_b16 v[2:3], v199 offset:49152
	ds_read_b64_tr_b16 v[4:5], v210 offset:51200
	ds_read_b64_tr_b16 v[6:7], v211 offset:49152
	ds_read_b64_tr_b16 v[8:9], v212 offset:51200
	s_waitcnt lgkmcnt(5)
	v_mfma_f32_32x32x16_bf16 v[96:111], v[10:13], v[156:159], v[96:111]
	ds_read_b64_tr_b16 v[10:11], v213 offset:49152
	ds_read_b64_tr_b16 v[12:13], v214 offset:51200
	ds_read_b64_tr_b16 v[160:161], v215 offset:49152
	ds_read_b64_tr_b16 v[162:163], v216 offset:51200
	s_waitcnt lgkmcnt(8)
	v_mfma_f32_32x32x16_bf16 v[80:95], v[112:115], v[156:159], v[80:95]
	v_max_f32_e32 v228, v226, v226
	s_and_saveexec_b64 s[22:23], vcc
	s_xor_b64 s[22:23], exec, s[22:23]
	s_cbranch_execz .LBB0_258_b
	ds_read2_b32 v[112:113], v218 offset0:58 offset1:59
	ds_read2_b32 v[114:115], v218 offset0:56 offset1:57
	ds_read2_b32 v[116:117], v218 offset0:50 offset1:51
	ds_read2_b32 v[118:119], v218 offset0:48 offset1:49
	ds_read2_b32 v[120:121], v218 offset0:26 offset1:27
	ds_read2_b32 v[122:123], v218 offset0:24 offset1:25
	ds_read2_b32 v[124:125], v218 offset0:18 offset1:19
	ds_read2_b32 v[126:127], v218 offset0:16 offset1:17
	ds_read2_b32 v[128:129], v218 offset0:42 offset1:43
	ds_read2_b32 v[130:131], v218 offset0:40 offset1:41
	ds_read2_b32 v[132:133], v218 offset0:34 offset1:35
	ds_read2_b32 v[134:135], v218 offset0:32 offset1:33
	ds_read2_b32 v[136:137], v218 offset0:10 offset1:11
	ds_read2_b32 v[138:139], v218 offset0:8 offset1:9
	ds_read2_b32 v[140:141], v218 offset0:2 offset1:3
	ds_read2_b32 v[142:143], v218 offset1:1
	s_nop 7
	s_nop 7
	s_nop 3
	s_waitcnt lgkmcnt(14)
	v_fma_f32 v96, v96, v178, v113
	s_waitcnt lgkmcnt(11)
	v_fma_f32 v80, v80, v178, v121
	v_fma_f32 v97, v97, v178, v112
	v_fma_f32 v81, v81, v178, v120
	v_fma_f32 v98, v98, v178, v115
	s_waitcnt lgkmcnt(10)
	v_fma_f32 v82, v82, v178, v123
	v_fma_f32 v99, v99, v178, v114
	v_fma_f32 v83, v83, v178, v122
	v_max3_f32 v112, v96, v97, v80
	v_fma_f32 v100, v100, v178, v117
	v_fma_f32 v101, v101, v178, v116
	v_fma_f32 v102, v102, v178, v119
	s_nop 0
	v_max3_f32 v113, v98, v99, v81
	v_fma_f32 v103, v103, v178, v118
	v_max3_f32 v112, v112, v82, v83
	s_waitcnt lgkmcnt(9)
	v_fma_f32 v84, v84, v178, v125
	v_fma_f32 v85, v85, v178, v124
	s_waitcnt lgkmcnt(8)
	v_fma_f32 v86, v86, v178, v127
	v_fma_f32 v87, v87, v178, v126
	v_max3_f32 v113, v113, v102, v103
	v_max3_f32 v112, v112, v100, v101
	s_waitcnt lgkmcnt(7)
	v_fma_f32 v104, v104, v178, v129
	v_fma_f32 v105, v105, v178, v128
	s_waitcnt lgkmcnt(6)
	v_fma_f32 v106, v106, v178, v131
	v_fma_f32 v107, v107, v178, v130
	v_max3_f32 v113, v113, v86, v87
	v_max3_f32 v112, v112, v84, v85
	s_waitcnt lgkmcnt(3)
	v_fma_f32 v88, v88, v178, v137
	v_fma_f32 v89, v89, v178, v136
	s_waitcnt lgkmcnt(2)
	v_fma_f32 v90, v90, v178, v139
	v_fma_f32 v91, v91, v178, v138
	v_max3_f32 v113, v113, v106, v107
	v_max3_f32 v112, v112, v104, v105
	v_fma_f32 v108, v108, v178, v133
	v_fma_f32 v109, v109, v178, v132
	v_fma_f32 v110, v110, v178, v135
	v_fma_f32 v111, v111, v178, v134
	s_nop 0
	v_max3_f32 v113, v113, v90, v91
	v_max3_f32 v112, v112, v88, v89
	s_waitcnt lgkmcnt(1)
	v_fma_f32 v92, v92, v178, v141
	v_fma_f32 v93, v93, v178, v140
	s_waitcnt lgkmcnt(0)
	v_fma_f32 v94, v94, v178, v143
	v_fma_f32 v95, v95, v178, v142
	v_max3_f32 v113, v113, v110, v111
	v_max3_f32 v112, v112, v108, v109
	s_nop 0
	v_max3_f32 v112, v112, v92, v93
	v_max3_f32 v113, v113, v94, v95
	s_nop 0
	v_max_f32_e32 v113, v113, v113
	v_max_f32_e32 v112, v112, v112
	v_max_f32_e32 v112, v112, v113
	v_mov_b32_e32 v113, v112
	s_nop 1
	v_permlane32_swap_b32_e32 v112, v113
	v_max_f32_e32 v113, v113, v113
	v_max_f32_e32 v112, v112, v112
	v_max_f32_e32 v112, v112, v113
	v_sub_f32_e32 v113, v112, v226
	v_cmp_lt_f32_e32 vcc, s45, v113
	s_cmp_eq_u64 vcc, 0
	v_max_f32_e32 v112, v228, v112
	s_cselect_b64 vcc, -1, 0
	v_cndmask_b32_e32 v227, v112, v226, vcc
	v_sub_f32 v112, v96, v227
	v_sub_f32 v128, v80, v227
	v_sub_f32 v113, v97, v227
	v_sub_f32 v129, v81, v227
	v_sub_f32 v114, v98, v227
	v_sub_f32 v130, v82, v227
	v_sub_f32 v115, v99, v227
	v_sub_f32 v131, v83, v227
	v_sub_f32 v116, v100, v227
	v_sub_f32 v132, v84, v227
	v_sub_f32 v117, v101, v227
	v_sub_f32 v133, v85, v227
	v_sub_f32 v118, v102, v227
	v_sub_f32 v134, v86, v227
	v_sub_f32 v119, v103, v227
	v_sub_f32 v135, v87, v227
	v_sub_f32 v120, v104, v227
	v_sub_f32 v136, v88, v227
	v_sub_f32 v121, v105, v227
	v_sub_f32 v137, v89, v227
	v_sub_f32 v122, v106, v227
	v_sub_f32 v138, v90, v227
	v_sub_f32 v123, v107, v227
	v_sub_f32 v139, v91, v227
	v_sub_f32 v124, v108, v227
	v_sub_f32 v140, v92, v227
	v_sub_f32 v125, v109, v227
	v_sub_f32 v141, v93, v227
	v_sub_f32 v126, v110, v227
	v_sub_f32 v142, v94, v227
	v_sub_f32 v127, v111, v227
	v_sub_f32 v143, v95, v227

.Ldf_far_nofix_b:
.LBB0_260_b:
	s_or_b64 exec, exec, s[22:23]
	v_cmp_neq_f32_e32 vcc, v227, v226
	ds_read_b64_tr_b16 v[80:81], v199 offset:53248
	ds_read_b64_tr_b16 v[82:83], v210 offset:55296
	ds_read_b64_tr_b16 v[84:85], v211 offset:53248
	ds_read_b64_tr_b16 v[86:87], v212 offset:55296
	ds_read_b64_tr_b16 v[88:89], v213 offset:53248
	ds_read_b64_tr_b16 v[90:91], v214 offset:55296
	ds_read_b64_tr_b16 v[92:93], v215 offset:53248
	ds_read_b64_tr_b16 v[94:95], v216 offset:55296
	v_exp_f32_e32 v104, v112
	v_exp_f32_e32 v105, v113
	v_exp_f32_e32 v106, v114
	v_exp_f32_e32 v107, v115
	v_exp_f32_e32 v108, v116
	v_exp_f32_e32 v109, v117
	v_exp_f32_e32 v110, v118
	v_exp_f32_e32 v111, v119
	s_cbranch_vccz .Ldf_norescale_b
	v_sub_f32_e32 v246, v226, v227
	v_exp_f32_e32 v246, v246
	s_nop 0
	v_mul_f32_e32 v219, v219, v246
	v_pk_mul_f32 v[78:79], v[78:79], v[246:247] op_sel_hi:[1,0]
	v_pk_mul_f32 v[76:77], v[76:77], v[246:247] op_sel_hi:[1,0]
	v_pk_mul_f32 v[74:75], v[74:75], v[246:247] op_sel_hi:[1,0]
	v_pk_mul_f32 v[72:73], v[72:73], v[246:247] op_sel_hi:[1,0]
	v_pk_mul_f32 v[70:71], v[70:71], v[246:247] op_sel_hi:[1,0]
	v_pk_mul_f32 v[68:69], v[68:69], v[246:247] op_sel_hi:[1,0]
	v_pk_mul_f32 v[66:67], v[66:67], v[246:247] op_sel_hi:[1,0]
	v_pk_mul_f32 v[64:65], v[64:65], v[246:247] op_sel_hi:[1,0]
	v_pk_mul_f32 v[62:63], v[62:63], v[246:247] op_sel_hi:[1,0]
	v_pk_mul_f32 v[60:61], v[60:61], v[246:247] op_sel_hi:[1,0]
	v_pk_mul_f32 v[58:59], v[58:59], v[246:247] op_sel_hi:[1,0]
	v_pk_mul_f32 v[56:57], v[56:57], v[246:247] op_sel_hi:[1,0]
	v_pk_mul_f32 v[54:55], v[54:55], v[246:247] op_sel_hi:[1,0]
	v_pk_mul_f32 v[52:53], v[52:53], v[246:247] op_sel_hi:[1,0]
	v_pk_mul_f32 v[50:51], v[50:51], v[246:247] op_sel_hi:[1,0]
	v_pk_mul_f32 v[48:49], v[48:49], v[246:247] op_sel_hi:[1,0]
	v_pk_mul_f32 v[46:47], v[46:47], v[246:247] op_sel_hi:[1,0]
	v_pk_mul_f32 v[44:45], v[44:45], v[246:247] op_sel_hi:[1,0]
	v_pk_mul_f32 v[42:43], v[42:43], v[246:247] op_sel_hi:[1,0]
	v_pk_mul_f32 v[40:41], v[40:41], v[246:247] op_sel_hi:[1,0]
	v_pk_mul_f32 v[38:39], v[38:39], v[246:247] op_sel_hi:[1,0]
	v_pk_mul_f32 v[36:37], v[36:37], v[246:247] op_sel_hi:[1,0]
	v_pk_mul_f32 v[34:35], v[34:35], v[246:247] op_sel_hi:[1,0]
	v_pk_mul_f32 v[32:33], v[32:33], v[246:247] op_sel_hi:[1,0]
	v_pk_mul_f32 v[30:31], v[30:31], v[246:247] op_sel_hi:[1,0]
	v_pk_mul_f32 v[28:29], v[28:29], v[246:247] op_sel_hi:[1,0]
	v_pk_mul_f32 v[26:27], v[26:27], v[246:247] op_sel_hi:[1,0]
	v_pk_mul_f32 v[24:25], v[24:25], v[246:247] op_sel_hi:[1,0]
	v_pk_mul_f32 v[22:23], v[22:23], v[246:247] op_sel_hi:[1,0]
	v_pk_mul_f32 v[20:21], v[20:21], v[246:247] op_sel_hi:[1,0]
	v_pk_mul_f32 v[18:19], v[18:19], v[246:247] op_sel_hi:[1,0]
	v_pk_mul_f32 v[16:17], v[16:17], v[246:247] op_sel_hi:[1,0]
; #define LAS __attribute__((address_space(3)))
; DI void diff_item(const Params& P, char* lds, int layer, int pair, int qt, int& tab_head) {
;     ...
;     for (int kt = 0; kt < nkt; ++kt) {
;         asm volatile("s_waitcnt vmcnt(0)" ::: "memory");
;         __syncthreads();
;         auto mid = [&]() { if (kt + 1 < nkt) issue(kt + 1, (kt + 1) & 1); };
;         if (64 * kt <= q0 + 32 * qs + 31) {
;             const bool far = (q0 + 32 * qs) - (64 * kt + 63) >= 1536;
;             const LAS float* tb = (const LAS float*)ctab + (qpos - 64 * kt - 4 * hh + 64 - 63);
;             lptr bufp = (lptr)lds + (kt & 1) * 32768;
;             diff_step(bufp, bufp + 16384, kx0, vl0, qf, m, l, O, tb, far, cfar, lane, mid);
;         } else mid();
.Ldf_norescale_b:
	v_add_f32_e32 v238, v104, v105
	v_add_f32_e32 v239, v106, v107
	v_add_f32_e32 v240, v108, v109
	v_add_f32_e32 v241, v110, v111
	v_add_f32_e32 v238, v238, v239
	v_add_f32_e32 v240, v240, v241
	v_cvt_pk_bf16_f32 v104, v104, v105
	v_cvt_pk_bf16_f32 v105, v106, v107
	v_cvt_pk_bf16_f32 v106, v108, v109
	v_cvt_pk_bf16_f32 v107, v110, v111
	v_add_f32_e32 v238, v238, v240
	v_add_f32_e32 v219, v219, v238
	s_waitcnt lgkmcnt(8)
	v_mfma_f32_32x32x16_bf16 v[64:79], v[2:5], v[104:107], v[64:79]
	v_exp_f32_e32 v96, v120
	v_exp_f32_e32 v97, v121
	v_exp_f32_e32 v98, v122
	v_exp_f32_e32 v99, v123
	v_mfma_f32_32x32x16_bf16 v[48:63], v[6:9], v[104:107], v[48:63]
	v_exp_f32_e32 v100, v124
	v_exp_f32_e32 v101, v125
	v_exp_f32_e32 v102, v126
	v_exp_f32_e32 v103, v127
	v_mfma_f32_32x32x16_bf16 v[32:47], v[10:13], v[104:107], v[32:47]
	v_add_f32_e32 v238, v96, v97
	v_add_f32_e32 v239, v98, v99
	v_add_f32_e32 v240, v100, v101
	v_add_f32_e32 v241, v102, v103
	v_add_f32_e32 v238, v238, v239
	v_add_f32_e32 v240, v240, v241
	v_mfma_f32_32x32x16_bf16 v[16:31], v[160:163], v[104:107], v[16:31]
	ds_read_b64_tr_b16 v[2:3], v199 offset:57344
	ds_read_b64_tr_b16 v[4:5], v210 offset:59392
	ds_read_b64_tr_b16 v[6:7], v211 offset:57344
	ds_read_b64_tr_b16 v[8:9], v212 offset:59392
	ds_read_b64_tr_b16 v[10:11], v213 offset:57344
	ds_read_b64_tr_b16 v[12:13], v214 offset:59392
	ds_read_b64_tr_b16 v[160:161], v215 offset:57344
	ds_read_b64_tr_b16 v[162:163], v216 offset:59392
	v_cvt_pk_bf16_f32 v96, v96, v97
	v_cvt_pk_bf16_f32 v97, v98, v99
	v_cvt_pk_bf16_f32 v98, v100, v101
	v_cvt_pk_bf16_f32 v99, v102, v103
	v_add_f32_e32 v238, v238, v240
	v_add_f32_e32 v219, v219, v238
	s_waitcnt lgkmcnt(8)
	v_mfma_f32_32x32x16_bf16 v[64:79], v[80:83], v[96:99], v[64:79]
	v_exp_f32_e32 v112, v128
	v_exp_f32_e32 v113, v129
	v_exp_f32_e32 v114, v130
	v_exp_f32_e32 v115, v131
	v_mfma_f32_32x32x16_bf16 v[48:63], v[84:87], v[96:99], v[48:63]
	v_exp_f32_e32 v116, v132
	v_exp_f32_e32 v117, v133
	v_exp_f32_e32 v118, v134
	v_exp_f32_e32 v119, v135
	v_mfma_f32_32x32x16_bf16 v[32:47], v[88:91], v[96:99], v[32:47]
	v_add_f32_e32 v238, v112, v113
	v_add_f32_e32 v239, v114, v115
	v_add_f32_e32 v240, v116, v117
	v_add_f32_e32 v241, v118, v119
	v_add_f32_e32 v238, v238, v239
	v_add_f32_e32 v240, v240, v241
	v_mfma_f32_32x32x16_bf16 v[16:31], v[92:95], v[96:99], v[16:31]
	ds_read_b64_tr_b16 v[80:81], v199 offset:61440
	ds_read_b64_tr_b16 v[82:83], v210 offset:63488
	ds_read_b64_tr_b16 v[84:85], v211 offset:61440
	ds_read_b64_tr_b16 v[86:87], v212 offset:63488
	ds_read_b64_tr_b16 v[88:89], v213 offset:61440
	ds_read_b64_tr_b16 v[90:91], v214 offset:63488
	ds_read_b64_tr_b16 v[92:93], v215 offset:61440
	ds_read_b64_tr_b16 v[94:95], v216 offset:63488
	v_cvt_pk_bf16_f32 v112, v112, v113
	v_cvt_pk_bf16_f32 v113, v114, v115
	v_cvt_pk_bf16_f32 v114, v116, v117
	v_cvt_pk_bf16_f32 v115, v118, v119
	v_add_f32_e32 v238, v238, v240
	v_add_f32_e32 v219, v219, v238
	s_waitcnt lgkmcnt(8)
	v_mfma_f32_32x32x16_bf16 v[64:79], v[2:5], v[112:115], v[64:79]
	v_exp_f32_e32 v120, v136
	v_exp_f32_e32 v121, v137
	v_exp_f32_e32 v122, v138
	v_exp_f32_e32 v123, v139
	v_mfma_f32_32x32x16_bf16 v[48:63], v[6:9], v[112:115], v[48:63]
	v_exp_f32_e32 v124, v140
	v_exp_f32_e32 v125, v141
	v_exp_f32_e32 v126, v142
	v_exp_f32_e32 v127, v143
	v_mfma_f32_32x32x16_bf16 v[32:47], v[10:13], v[112:115], v[32:47]
	v_add_f32_e32 v238, v120, v121
	v_add_f32_e32 v239, v122, v123
	v_add_f32_e32 v240, v124, v125
	v_add_f32_e32 v241, v126, v127
	v_add_f32_e32 v238, v238, v239
	v_add_f32_e32 v240, v240, v241
	v_mfma_f32_32x32x16_bf16 v[16:31], v[160:163], v[112:115], v[16:31]
	v_cvt_pk_bf16_f32 v120, v120, v121
	v_cvt_pk_bf16_f32 v121, v122, v123
	v_cvt_pk_bf16_f32 v122, v124, v125
	v_cvt_pk_bf16_f32 v123, v126, v127
	v_add_f32_e32 v238, v238, v240
	v_add_f32_e32 v219, v219, v238
	s_waitcnt lgkmcnt(6)
	v_mfma_f32_32x32x16_bf16 v[64:79], v[80:83], v[120:123], v[64:79]
	s_waitcnt lgkmcnt(4)
	v_mfma_f32_32x32x16_bf16 v[48:63], v[84:87], v[120:123], v[48:63]
	s_waitcnt lgkmcnt(2)
	v_mfma_f32_32x32x16_bf16 v[32:47], v[88:91], v[120:123], v[32:47]
	s_waitcnt lgkmcnt(0)
	v_mfma_f32_32x32x16_bf16 v[16:31], v[92:95], v[120:123], v[16:31]
.LBB0_263_b:
	s_andn2_saveexec_b64 s[22:23], s[40:41]
	s_cbranch_execz .LBB0_252_b
	v_cmp_gt_u32_e32 vcc, s49, v0
	s_and_saveexec_b64 s[40:41], vcc
	s_cbranch_execz .LBB0_251_b
	s_mov_b32 s72, s63
	s_mov_b32 m0, s72
	s_nop 0
	global_load_lds_dwordx4 v170, s[64:65]
	s_add_u32 s72, s63, 0x4000
	s_mov_b32 m0, s72
	s_nop 0
	global_load_lds_dwordx4 v170, s[70:71]
	s_add_u32 s72, s63, 0x400
	s_mov_b32 m0, s72
	s_nop 0
	global_load_lds_dwordx4 v172, s[64:65]
	s_add_u32 s72, s63, 0x4400
	s_mov_b32 m0, s72
	s_nop 0
	global_load_lds_dwordx4 v172, s[70:71]
	s_add_u32 s64, s64, 0xe0000
	s_addc_u32 s65, s65, 0
	s_add_u32 s70, s70, 0xe0000
	s_addc_u32 s71, s71, 0
	s_branch .LBB0_251_b

; #define LAS __attribute__((address_space(3)))
; DI void diff_item(const Params& P, char* lds, int layer, int pair, int qt, int& tab_head) {
;     ...
;     for (int kt = 0; kt < nkt; ++kt) {
;         asm volatile("s_waitcnt vmcnt(0)" ::: "memory");
;         __syncthreads();
;         auto mid = [&]() { if (kt + 1 < nkt) issue(kt + 1, (kt + 1) & 1); };
;         if (64 * kt <= q0 + 32 * qs + 31) {
;             const bool far = (q0 + 32 * qs) - (64 * kt + 63) >= 1536;
;             const LAS float* tb = (const LAS float*)ctab + (qpos - 64 * kt - 4 * hh + 64 - 63);
;             lptr bufp = (lptr)lds + (kt & 1) * 32768;
;             diff_step(bufp, bufp + 16384, kx0, vl0, qf, m, l, O, tb, far, cfar, lane, mid);
;         } else mid();
;     }
.LBB0_252_b:
	s_or_b64 exec, exec, s[22:23]
	s_add_i32 s50, s50, 64
	v_cmp_eq_u32_e32 vcc, s51, v220
	v_subrev_u32_e32 v217, 64, v217
	v_add_u32_e32 v218, 0xffffff00, v218
	s_or_b64 s[0:1], vcc, s[0:1]
	v_mov_b32_e32 v226, v227
	s_andn2_b64 exec, exec, s[0:1]
	s_cbranch_execz .LBB0_266
	s_branch .Ldu_A
